# B3 retention intra-chunk loop: the 8 K-row and 8 V-row global loads of a 32-key step are issued together at the top of the iteration instead of one at a time before their MFMAs
# speedup vs baseline: 1.0271x; 1.0024x over previous
; __device__ void ret_out_item(const P& p, int bh, int c) {
;     ...
;   for (int ms = 0; ms <= w; ++ms) {
;     f32x4 sacc[2][2];
; #pragma unroll
;     for (int kt = 0; kt < 2; ++kt) {
;       const int row = 32 * ms + 8 * (li >> 2) + 4 * kt + (li & 3);
; #pragma unroll
;       for (int ns = 0; ns < 2; ++ns) sacc[kt][ns] = (f32x4){0.f, 0.f, 0.f, 0.f};
; #pragma unroll
;       for (int kk = 0; kk < 4; ++kk) {
;         const bf16x8 kf = *(const bf16x8*)(Kp + (size_t)row * 128 + (kk * 4 + g) * 8);
; #pragma unroll
;         for (int ns = 0; ns < 2; ++ns) sacc[kt][ns] = __builtin_amdgcn_mfma_f32_16x16x32_bf16(kf, qf[ns][kk], sacc[kt][ns], 0, 0, 0);
;       }
;     }
;     bf16x8 pf[2];
; #pragma unroll
;     for (int ns = 0; ns < 2; ++ns) {
;       const int n = 32 * w + 16 * ns + li;
;       float pv[8];
; #pragma unroll
;       for (int kt = 0; kt < 2; ++kt)
; #pragma unroll
;         for (int r = 0; r < 4; ++r) {
;           const int m = 32 * ms + 8 * g + 4 * kt + r;
;           const float dec = (n >= m) ? exp2f((float)(n - m) * lg) : 0.f;
;           pv[kt * 4 + r] = sacc[kt][ns][r] * dec;
;         }
;       u32x4 u;
;       u.x = pk_bf16(pv[0], pv[1]); u.y = pk_bf16(pv[2], pv[3]); u.z = pk_bf16(pv[4], pv[5]); u.w = pk_bf16(pv[6], pv[7]);
;       pf[ns] = *(bf16x8*)&u;
;     }
; #pragma unroll
;     for (int es = 0; es < 8; ++es) {
;       const bf16x8 vf = *(const bf16x8*)(VT + (size_t)(es * 16 + li) * 4096 + 32 * ms + 8 * g);
; #pragma unroll
;       for (int ns = 0; ns < 2; ++ns) acc[es][ns] = __builtin_amdgcn_mfma_f32_16x16x32_bf16(vf, pf[ns], acc[es][ns], 0, 0, 0);
.LBB0_765:
	s_waitcnt vmcnt(16)
	v_lshl_add_u64 v[128:129], v[132:133], 0, v[0:1]
	v_lshl_add_u64 v[148:149], v[134:135], 0, v[0:1]
	global_load_dwordx4 v[192:195], v[128:129], off offset:-128
	global_load_dwordx4 v[196:199], v[128:129], off offset:-64
	global_load_dwordx4 v[200:203], v[128:129], off
	global_load_dwordx4 v[204:207], v[128:129], off offset:64
	global_load_dwordx4 v[220:223], v[148:149], off offset:-128
	global_load_dwordx4 v[224:227], v[148:149], off offset:-64
	global_load_dwordx4 v[228:231], v[148:149], off
	global_load_dwordx4 v[232:235], v[148:149], off offset:64
	v_lshl_add_u64 v[188:189], v[2:3], 0, v[0:1]
	s_mov_b32 s99, 0
	s_mov_b32 s98, 0x1fa84000
	v_lshl_add_u64 v[190:191], v[188:189], 0, s[98:99]
	global_load_dwordx4 v[156:159], v[190:191], off
	s_mov_b32 s98, 0x1faa4000
	v_lshl_add_u64 v[190:191], v[188:189], 0, s[98:99]
	global_load_dwordx4 v[160:163], v[190:191], off
	s_mov_b32 s98, 0x1fac4000
	v_lshl_add_u64 v[190:191], v[188:189], 0, s[98:99]
	global_load_dwordx4 v[164:167], v[190:191], off
	s_mov_b32 s98, 0x1fae4000
	v_lshl_add_u64 v[190:191], v[188:189], 0, s[98:99]
	global_load_dwordx4 v[168:171], v[190:191], off
	s_mov_b32 s98, 0x1fb04000
	v_lshl_add_u64 v[190:191], v[188:189], 0, s[98:99]
	global_load_dwordx4 v[172:175], v[190:191], off
	s_mov_b32 s98, 0x1fb24000
	v_lshl_add_u64 v[190:191], v[188:189], 0, s[98:99]
	global_load_dwordx4 v[176:179], v[190:191], off
	s_mov_b32 s98, 0x1fb44000
	v_lshl_add_u64 v[190:191], v[188:189], 0, s[98:99]
	global_load_dwordx4 v[180:183], v[190:191], off
	s_mov_b32 s98, 0x1fb64000
	v_lshl_add_u64 v[190:191], v[188:189], 0, s[98:99]
	global_load_dwordx4 v[184:187], v[190:191], off
	v_add_u32_e32 v152, 7, v137
	v_add_u32_e32 v139, -1, v139
	v_lshl_add_u64 v[132:133], v[132:133], 0, s[84:85]
	v_lshl_add_u64 v[134:135], v[134:135], 0, s[84:85]
	s_waitcnt vmcnt(15)
	v_mfma_f32_16x16x32_bf16 v[120:123], v[192:195], v[84:87], 0
	v_mfma_f32_16x16x32_bf16 v[116:119], v[192:195], v[100:103], 0
	s_waitcnt vmcnt(14)
	v_mfma_f32_16x16x32_bf16 v[120:123], v[196:199], v[88:91], v[120:123]
	v_mfma_f32_16x16x32_bf16 v[116:119], v[196:199], v[104:107], v[116:119]
	s_waitcnt vmcnt(13)
	v_mfma_f32_16x16x32_bf16 v[120:123], v[200:203], v[92:95], v[120:123]
	v_mfma_f32_16x16x32_bf16 v[116:119], v[200:203], v[108:111], v[116:119]
	s_waitcnt vmcnt(12)
	v_mfma_f32_16x16x32_bf16 v[128:131], v[204:207], v[96:99], v[120:123]
	v_mfma_f32_16x16x32_bf16 v[124:127], v[204:207], v[112:115], v[116:119]
	s_waitcnt vmcnt(11)
	v_mfma_f32_16x16x32_bf16 v[120:123], v[220:223], v[84:87], 0
	v_mfma_f32_16x16x32_bf16 v[116:119], v[220:223], v[100:103], 0
	s_waitcnt vmcnt(10)
	v_mfma_f32_16x16x32_bf16 v[120:123], v[224:227], v[88:91], v[120:123]
	v_mfma_f32_16x16x32_bf16 v[116:119], v[224:227], v[104:107], v[116:119]
	s_waitcnt vmcnt(9)
	v_mfma_f32_16x16x32_bf16 v[120:123], v[228:231], v[92:95], v[120:123]
	v_mfma_f32_16x16x32_bf16 v[144:147], v[228:231], v[108:111], v[116:119]
	s_waitcnt vmcnt(8)
	v_mfma_f32_16x16x32_bf16 v[116:119], v[232:235], v[96:99], v[120:123]
	v_mfma_f32_16x16x32_bf16 v[120:123], v[232:235], v[112:115], v[144:147]
	s_nop 4
	v_add_u32_e32 v144, -16, v141
	v_cvt_f32_i32_e32 v144, v144
	s_waitcnt lgkmcnt(0)
	v_mul_f32_e32 v145, s24, v144
	v_cmp_gt_f32_e32 vcc, s53, v145
	s_nop 1
	v_cndmask_b32_e32 v145, 0, v242, vcc
	v_fmac_f32_e32 v145, s24, v144
	v_exp_f32_e32 v144, v145
	v_cndmask_b32_e32 v145, 0, v241, vcc
	v_cmp_ge_i32_e32 vcc, v138, v137
	v_ldexp_f32 v144, v144, v145
	s_nop 0
	v_cndmask_b32_e32 v144, 0, v144, vcc
	v_mul_f32_e32 v128, v144, v128
	v_subrev_u32_e32 v144, 17, v141
	v_cvt_f32_i32_e32 v144, v144
	v_cmp_gt_i32_e32 vcc, v138, v137
	v_mul_f32_e32 v145, s24, v144
	v_cmp_gt_f32_e64 s[0:1], s53, v145
	s_nop 1
	v_cndmask_b32_e64 v146, 0, v242, s[0:1]
	v_fmac_f32_e32 v146, s24, v144
	v_exp_f32_e32 v144, v146
	v_cndmask_b32_e64 v145, 0, v241, s[0:1]
	v_ldexp_f32 v144, v144, v145
	v_subrev_u32_e32 v145, 18, v141
	v_cvt_f32_i32_e32 v145, v145
	v_cndmask_b32_e32 v144, 0, v144, vcc
	v_mul_f32_e32 v129, v144, v129
	v_add_u32_e32 v144, 2, v137
	v_mul_f32_e32 v146, s24, v145
	v_cmp_gt_f32_e32 vcc, s53, v146
	s_nop 1
	v_cndmask_b32_e32 v147, 0, v242, vcc
	v_fmac_f32_e32 v147, s24, v145
	v_exp_f32_e32 v145, v147
	v_cndmask_b32_e32 v146, 0, v241, vcc
	v_cmp_ge_i32_e32 vcc, v138, v144
	v_ldexp_f32 v145, v145, v146
	v_subrev_u32_e32 v146, 19, v141
	v_cvt_f32_i32_e32 v146, v146
	v_cndmask_b32_e32 v145, 0, v145, vcc
	v_mul_f32_e32 v130, v145, v130
	v_add_u32_e32 v145, 3, v137
	v_mul_f32_e32 v147, s24, v146
	v_cmp_gt_f32_e32 vcc, s53, v147
	s_nop 1
	v_cndmask_b32_e32 v148, 0, v242, vcc
	v_fmac_f32_e32 v148, s24, v146
	v_exp_f32_e32 v146, v148
	v_cndmask_b32_e32 v147, 0, v241, vcc
	v_cmp_ge_i32_e32 vcc, v138, v145
	v_ldexp_f32 v146, v146, v147
	v_subrev_u32_e32 v147, 20, v141
	v_cvt_f32_i32_e32 v147, v147
	v_cndmask_b32_e32 v146, 0, v146, vcc
	v_mul_f32_e32 v131, v146, v131
	v_add_u32_e32 v146, 4, v137
	v_mul_f32_e32 v148, s24, v147
	v_cmp_gt_f32_e32 vcc, s53, v148
	s_nop 1
	v_cndmask_b32_e32 v149, 0, v242, vcc
	v_fmac_f32_e32 v149, s24, v147
	v_exp_f32_e32 v147, v149
	v_cndmask_b32_e32 v148, 0, v241, vcc
	v_cmp_ge_i32_e32 vcc, v138, v146
	v_ldexp_f32 v147, v147, v148
	s_nop 0
	v_cndmask_b32_e32 v147, 0, v147, vcc
	v_mul_f32_e32 v147, v147, v116
	v_subrev_u32_e32 v116, 21, v141
	v_cvt_f32_i32_e32 v116, v116
	v_add_u32_e32 v148, 5, v137
	v_mul_f32_e32 v149, s24, v116
	v_cmp_gt_f32_e32 vcc, s53, v149
	s_nop 1
	v_cndmask_b32_e32 v150, 0, v242, vcc
	v_fmac_f32_e32 v150, s24, v116
	v_exp_f32_e32 v116, v150
	v_cndmask_b32_e32 v149, 0, v241, vcc
	v_cmp_ge_i32_e32 vcc, v138, v148
	v_add_u32_e32 v150, 6, v137
; __device__ void ret_out_item(const P& p, int bh, int c) {
;     ...
;     for (int ns = 0; ns < 2; ++ns) {
;       const int n = 32 * w + 16 * ns + li;
;       float pv[8];
; #pragma unroll
;       for (int kt = 0; kt < 2; ++kt)
; #pragma unroll
;         for (int r = 0; r < 4; ++r) {
;           const int m = 32 * ms + 8 * g + 4 * kt + r;
;           const float dec = (n >= m) ? exp2f((float)(n - m) * lg) : 0.f;
;           pv[kt * 4 + r] = sacc[kt][ns][r] * dec;
;         }
;       u32x4 u;
;       u.x = pk_bf16(pv[0], pv[1]); u.y = pk_bf16(pv[2], pv[3]); u.z = pk_bf16(pv[4], pv[5]); u.w = pk_bf16(pv[6], pv[7]);
;       pf[ns] = *(bf16x8*)&u;
;     }
; #pragma unroll
;     for (int es = 0; es < 8; ++es) {
;       const bf16x8 vf = *(const bf16x8*)(VT + (size_t)(es * 16 + li) * 4096 + 32 * ms + 8 * g);
; #pragma unroll
;       for (int ns = 0; ns < 2; ++ns) acc[es][ns] = __builtin_amdgcn_mfma_f32_16x16x32_bf16(vf, pf[ns], acc[es][ns], 0, 0, 0);
;     }
	v_ldexp_f32 v116, v116, v149
	v_cndmask_b32_e32 v116, 0, v116, vcc
	v_mul_f32_e32 v149, v116, v117
	v_subrev_u32_e32 v116, 22, v141
	v_cvt_f32_i32_e32 v116, v116
	v_mul_f32_e32 v117, s24, v116
	v_cmp_gt_f32_e32 vcc, s53, v117
	s_nop 1
	v_cndmask_b32_e32 v151, 0, v242, vcc
	v_fmac_f32_e32 v151, s24, v116
	v_exp_f32_e32 v116, v151
	v_cndmask_b32_e32 v117, 0, v241, vcc
	v_cmp_ge_i32_e32 vcc, v138, v150
	v_ldexp_f32 v116, v116, v117
	s_nop 0
	v_cndmask_b32_e32 v116, 0, v116, vcc
	v_mul_f32_e32 v151, v116, v118
	v_subrev_u32_e32 v116, 23, v141
	v_cvt_f32_i32_e32 v116, v116
	v_mul_f32_e32 v117, s24, v116
	v_cmp_gt_f32_e32 vcc, s53, v117
	s_nop 1
	v_cndmask_b32_e32 v118, 0, v242, vcc
	v_fmac_f32_e32 v118, s24, v116
	v_exp_f32_e32 v116, v118
	v_cndmask_b32_e32 v117, 0, v241, vcc
	v_cmp_ge_i32_e32 vcc, v138, v152
	v_cvt_pk_bf16_f32 v118, v147, v149
	v_ldexp_f32 v116, v116, v117
	v_cndmask_b32_e32 v116, 0, v116, vcc
	v_mul_f32_e32 v119, v116, v119
	v_cvt_pk_bf16_f32 v116, v128, v129
	v_cvt_f32_i32_e32 v128, v141
	v_cvt_pk_bf16_f32 v117, v130, v131
	v_cvt_pk_bf16_f32 v119, v151, v119
	v_mul_f32_e32 v129, s24, v128
	v_cmp_gt_f32_e32 vcc, s53, v129
	s_nop 1
	v_cndmask_b32_e32 v130, 0, v242, vcc
	v_fmac_f32_e32 v130, s24, v128
	v_exp_f32_e32 v128, v130
	v_cndmask_b32_e32 v129, 0, v241, vcc
	v_cmp_ge_i32_e32 vcc, v140, v137
	v_ldexp_f32 v128, v128, v129
	s_nop 0
	v_cndmask_b32_e32 v128, 0, v128, vcc
	v_mul_f32_e32 v124, v128, v124
	v_add_u32_e32 v128, -1, v141
	v_cvt_f32_i32_e32 v128, v128
	v_cmp_gt_i32_e32 vcc, v140, v137
	v_add_u32_e32 v137, 32, v137
	v_mul_f32_e32 v129, s24, v128
	v_cmp_gt_f32_e64 s[0:1], s53, v129
	s_nop 1
	v_cndmask_b32_e64 v129, 0, v242, s[0:1]
	v_fmac_f32_e32 v129, s24, v128
	v_exp_f32_e32 v128, v129
	v_cndmask_b32_e64 v129, 0, v241, s[0:1]
	s_mov_b32 s0, 0x1fa84000
	v_ldexp_f32 v128, v128, v129
	v_cndmask_b32_e32 v128, 0, v128, vcc
	v_mul_f32_e32 v125, v128, v125
	v_add_u32_e32 v128, -2, v141
	v_cvt_f32_i32_e32 v128, v128
	v_mul_f32_e32 v129, s24, v128
	v_cmp_gt_f32_e32 vcc, s53, v129
	s_nop 1
	v_cndmask_b32_e32 v129, 0, v242, vcc
	v_fmac_f32_e32 v129, s24, v128
	v_exp_f32_e32 v128, v129
	v_cndmask_b32_e32 v129, 0, v241, vcc
	v_cmp_ge_i32_e32 vcc, v140, v144
	v_ldexp_f32 v128, v128, v129
	s_nop 0
	v_cndmask_b32_e32 v128, 0, v128, vcc
	v_mul_f32_e32 v126, v128, v126
	v_add_u32_e32 v128, -3, v141
	v_cvt_f32_i32_e32 v128, v128
	v_mul_f32_e32 v129, s24, v128
	v_cmp_gt_f32_e32 vcc, s53, v129
	s_nop 1
	v_cndmask_b32_e32 v129, 0, v242, vcc
	v_fmac_f32_e32 v129, s24, v128
	v_exp_f32_e32 v128, v129
	v_cndmask_b32_e32 v129, 0, v241, vcc
	v_cmp_ge_i32_e32 vcc, v140, v145
	v_ldexp_f32 v128, v128, v129
	s_nop 0
	v_cndmask_b32_e32 v128, 0, v128, vcc
	v_mul_f32_e32 v127, v128, v127
	v_add_u32_e32 v128, -4, v141
	v_cvt_f32_i32_e32 v128, v128
	v_mul_f32_e32 v129, s24, v128
	v_cmp_gt_f32_e32 vcc, s53, v129
	s_nop 1
	v_cndmask_b32_e32 v129, 0, v242, vcc
	v_fmac_f32_e32 v129, s24, v128
	v_exp_f32_e32 v128, v129
	v_cndmask_b32_e32 v129, 0, v241, vcc
	v_cmp_ge_i32_e32 vcc, v140, v146
	v_ldexp_f32 v128, v128, v129
	s_nop 0
	v_cndmask_b32_e32 v128, 0, v128, vcc
	v_mul_f32_e32 v128, v128, v120
	v_add_u32_e32 v120, -5, v141
	v_cvt_f32_i32_e32 v120, v120
	v_mul_f32_e32 v129, s24, v120
	v_cmp_gt_f32_e32 vcc, s53, v129
	s_nop 1
	v_cndmask_b32_e32 v129, 0, v242, vcc
	v_fmac_f32_e32 v129, s24, v120
	v_exp_f32_e32 v120, v129
	v_cndmask_b32_e32 v129, 0, v241, vcc
	v_cmp_ge_i32_e32 vcc, v140, v148
	v_ldexp_f32 v120, v120, v129
	s_nop 0
	v_cndmask_b32_e32 v120, 0, v120, vcc
	v_mul_f32_e32 v129, v120, v121
	v_add_u32_e32 v120, -6, v141
	v_cvt_f32_i32_e32 v120, v120
	v_mul_f32_e32 v121, s24, v120
	v_cmp_gt_f32_e32 vcc, s53, v121
	s_nop 1
	v_cndmask_b32_e32 v121, 0, v242, vcc
	v_fmac_f32_e32 v121, s24, v120
	v_exp_f32_e32 v120, v121
	v_cndmask_b32_e32 v121, 0, v241, vcc
	v_cmp_ge_i32_e32 vcc, v140, v150
	v_ldexp_f32 v120, v120, v121
	s_nop 0
	v_cndmask_b32_e32 v120, 0, v120, vcc
	v_mul_f32_e32 v130, v120, v122
	v_add_u32_e32 v120, -7, v141
	v_cvt_f32_i32_e32 v120, v120
	v_cvt_pk_bf16_f32 v122, v128, v129
	v_subrev_u32_e32 v141, 32, v141
	v_mul_f32_e32 v121, s24, v120
	v_cmp_gt_f32_e32 vcc, s53, v121
	s_nop 1
	v_cndmask_b32_e32 v121, 0, v242, vcc
	v_fmac_f32_e32 v121, s24, v120
	v_exp_f32_e32 v120, v121
	v_cndmask_b32_e32 v121, 0, v241, vcc
	v_cmp_ge_i32_e32 vcc, v140, v152
	v_ldexp_f32 v120, v120, v121
	s_nop 0
	v_cndmask_b32_e32 v120, 0, v120, vcc
	v_mul_f32_e32 v123, v120, v123
	v_cvt_pk_bf16_f32 v120, v124, v125
	v_cvt_pk_bf16_f32 v121, v126, v127
	v_cvt_pk_bf16_f32 v123, v130, v123
	v_lshl_add_u64 v[2:3], v[2:3], 0, 64
	v_cmp_eq_u32_e32 vcc, 0, v139
	s_waitcnt vmcnt(7)
	v_mfma_f32_16x16x32_bf16 v[60:63], v[156:159], v[116:119], v[60:63]
	v_mfma_f32_16x16x32_bf16 v[48:51], v[156:159], v[120:123], v[48:51]
	s_or_b64 s[20:21], vcc, s[20:21]
	s_waitcnt vmcnt(6)
	v_mfma_f32_16x16x32_bf16 v[52:55], v[160:163], v[116:119], v[52:55]
	v_mfma_f32_16x16x32_bf16 v[44:47], v[160:163], v[120:123], v[44:47]
	s_waitcnt vmcnt(5)
	v_mfma_f32_16x16x32_bf16 v[56:59], v[164:167], v[116:119], v[56:59]
	v_mfma_f32_16x16x32_bf16 v[40:43], v[164:167], v[120:123], v[40:43]
	s_waitcnt vmcnt(4)
	v_mfma_f32_16x16x32_bf16 v[64:67], v[168:171], v[116:119], v[64:67]
	v_mfma_f32_16x16x32_bf16 v[36:39], v[168:171], v[120:123], v[36:39]
	s_waitcnt vmcnt(3)
	v_mfma_f32_16x16x32_bf16 v[68:71], v[172:175], v[116:119], v[68:71]
	v_mfma_f32_16x16x32_bf16 v[32:35], v[172:175], v[120:123], v[32:35]
	s_waitcnt vmcnt(2)
	v_mfma_f32_16x16x32_bf16 v[72:75], v[176:179], v[116:119], v[72:75]
	v_mfma_f32_16x16x32_bf16 v[28:31], v[176:179], v[120:123], v[28:31]
	s_waitcnt vmcnt(1)
	v_mfma_f32_16x16x32_bf16 v[76:79], v[180:183], v[116:119], v[76:79]
	v_mfma_f32_16x16x32_bf16 v[24:27], v[180:183], v[120:123], v[24:27]
	s_waitcnt vmcnt(0)
	v_mfma_f32_16x16x32_bf16 v[80:83], v[184:187], v[116:119], v[80:83]
	v_mfma_f32_16x16x32_bf16 v[20:23], v[184:187], v[120:123], v[20:23]
	s_mov_b32 s0, 0x1fb44000
	s_andn2_b64 exec, exec, s[20:21]
	s_cbranch_execnz .LBB0_765
	s_or_b64 exec, exec, s[20:21]
	s_branch .LBB0_760
